# v59 stack plus unit-loop tile scheduler: division by the constant group size 8 done with shift/mask instead of the v_rcp_iflag runtime division
# speedup vs baseline: 1.0207x; 1.0090x over previous
;     __host__ __device__ bool next(int i, Unit& u) const {
;         const long L = (long)i * G + c; if (L >= nwg) return false;
;         int wgid = (int)L; { const int q = nwg / NXCD, r = nwg % NXCD, xcd = wgid % NXCD, off = wgid / NXCD; wgid = (xcd < r ? xcd * (q + 1) : r * (q + 1) + (xcd - r) * q) + off; }
;         const int nig = WGM * nN, gid = wgid / nig, fm = gid * WGM, gsz = (nM - fm) < WGM ? (nM - fm) : WGM;
;         u.pm = fm + ((wgid % nig) % gsz); u.pn = (wgid % nig) / gsz; return true;
;     }
.LBB0_130:
	s_add_i32 s72, s72, 1
	s_mul_i32 s0, s72, s73
	s_mul_hi_u32 s1, s72, s28
	s_add_i32 s1, s1, s0
	s_mul_i32 s0, s72, s28
	s_add_u32 s44, s0, s2
	s_addc_u32 s45, s1, s29
	v_cmp_gt_i64_e32 vcc, s[44:45], v[146:147]
	v_cmp_lt_i64_e64 s[0:1], s[44:45], v[144:145]
	s_cbranch_vccnz .LBB0_132
	s_ashr_i32 s40, s44, 31
	s_lshr_b32 s40, s40, 29
	s_add_i32 s40, s44, s40
	s_ashr_i32 s41, s40, 3
	s_and_b32 s40, s40, -8
	s_sub_i32 s40, s44, s40
	s_cmp_lt_i32 s40, 0
	s_cselect_b32 s42, s67, 0x2c0
	s_mul_i32 s40, s40, s42
	s_add_i32 s40, s40, s41
	s_mul_hi_i32 s41, s40, 0x2e8ba2e9
	s_lshr_b32 s42, s41, 31
	s_ashr_i32 s41, s41, 5
	s_add_i32 s41, s41, s42
	s_lshl_b32 s42, s41, 3
	s_mulk_i32 s41, 0xb0
	s_sub_i32 s41, s40, s41
	s_lshr_b32 s40, s41, 3
	s_and_b32 s41, s41, 7
	s_add_i32 s42, s42, s41

;     __host__ __device__ bool next(int i, Unit& u) const {
;     ...
;         int wgid = (int)L; { const int q = nwg / NXCD, r = nwg % NXCD, xcd = wgid % NXCD, off = wgid / NXCD; wgid = (xcd < r ? xcd * (q + 1) : r * (q + 1) + (xcd - r) * q) + off; }
;         const int nig = WGM * nN, gid = wgid / nig, fm = gid * WGM, gsz = (nM - fm) < WGM ? (nM - fm) : WGM;
;         u.pm = fm + ((wgid % nig) % gsz); u.pn = (wgid % nig) / gsz; return true;
.LBB0_205:
	s_ashr_i32 s6, s44, 3
	s_add_i32 s6, s60, s6
	s_ashr_i32 s7, s6, 31
	s_lshr_b32 s7, s7, 27
	s_add_i32 s7, s6, s7
	s_ashr_i32 s44, s7, 5
	s_lshl_b32 s44, s44, 3
	s_andn2_b32 s7, s7, 31
	s_sub_i32 s6, s6, s7
	s_lshr_b32 s76, s6, 3
	s_and_b32 s6, s6, 7
	s_add_i32 s77, s44, s6

;     __host__ __device__ bool next(int i, Unit& u) const {
;     ...
;         int wgid = (int)L; { const int q = nwg / NXCD, r = nwg % NXCD, xcd = wgid % NXCD, off = wgid / NXCD; wgid = (xcd < r ? xcd * (q + 1) : r * (q + 1) + (xcd - r) * q) + off; }
;         const int nig = WGM * nN, gid = wgid / nig, fm = gid * WGM, gsz = (nM - fm) < WGM ? (nM - fm) : WGM;
;         u.pm = fm + ((wgid % nig) % gsz); u.pn = (wgid % nig) / gsz; return true;
.LBB0_298:
	s_ashr_i32 s5, s5, 3
	s_add_i32 s5, s45, s5
	s_ashr_i32 s6, s5, 31
	s_lshr_b32 s6, s6, 26
	s_add_i32 s6, s5, s6
	s_ashr_i32 s45, s6, 6
	s_lshl_b32 s45, s45, 3
	s_andn2_b32 s6, s6, 63
	s_sub_i32 s5, s5, s6
	s_lshr_b32 s46, s5, 3
	s_and_b32 s5, s5, 7
	s_add_i32 s48, s45, s5

;     __host__ __device__ bool next(int i, Unit& u) const {
;     ...
;         int wgid = (int)L; { const int q = nwg / NXCD, r = nwg % NXCD, xcd = wgid % NXCD, off = wgid / NXCD; wgid = (xcd < r ? xcd * (q + 1) : r * (q + 1) + (xcd - r) * q) + off; }
;         const int nig = WGM * nN, gid = wgid / nig, fm = gid * WGM, gsz = (nM - fm) < WGM ? (nM - fm) : WGM;
;         u.pm = fm + ((wgid % nig) % gsz); u.pn = (wgid % nig) / gsz; return true;
.LBB0_733:
	s_ashr_i32 s16, s18, 3
	s_add_i32 s16, s20, s16
	s_ashr_i32 s17, s16, 31
	s_lshr_b32 s17, s17, 27
	s_add_i32 s17, s16, s17
	s_ashr_i32 s18, s17, 5
	s_lshl_b32 s18, s18, 3
	s_andn2_b32 s17, s17, 31
	s_sub_i32 s17, s16, s17
	s_lshr_b32 s16, s17, 3
	s_and_b32 s17, s17, 7
	s_add_i32 s18, s18, s17

;     __host__ __device__ bool next(int i, Unit& u) const {
;         const long L = (long)i * G + c; if (L >= nwg) return false;
;         int wgid = (int)L; { const int q = nwg / NXCD, r = nwg % NXCD, xcd = wgid % NXCD, off = wgid / NXCD; wgid = (xcd < r ? xcd * (q + 1) : r * (q + 1) + (xcd - r) * q) + off; }
;         const int nig = WGM * nN, gid = wgid / nig, fm = gid * WGM, gsz = (nM - fm) < WGM ? (nM - fm) : WGM;
;         u.pm = fm + ((wgid % nig) % gsz); u.pn = (wgid % nig) / gsz; return true;
.LBB0_814:
	s_add_i32 s54, s54, 1
	s_mul_i32 s0, s54, s55
	s_mul_hi_u32 s1, s54, s28
	s_add_i32 s1, s1, s0
	s_mul_i32 s0, s54, s28
	s_add_u32 s14, s0, s2
	s_addc_u32 s15, s1, s29
	v_cmp_gt_i64_e32 vcc, s[14:15], v[146:147]
	v_cmp_lt_i64_e64 s[0:1], s[14:15], v[144:145]
	s_cbranch_vccnz .LBB0_816
	s_ashr_i32 s10, s14, 31
	s_lshr_b32 s10, s10, 29
	s_add_i32 s10, s14, s10
	s_ashr_i32 s11, s10, 3
	s_and_b32 s10, s10, -8
	s_sub_i32 s10, s14, s10
	s_cmp_lt_i32 s10, 0
	s_cselect_b32 s12, s47, 0x2c0
	s_mul_i32 s10, s10, s12
	s_add_i32 s10, s10, s11
	s_mul_hi_i32 s11, s10, 0x2e8ba2e9
	s_lshr_b32 s12, s11, 31
	s_ashr_i32 s11, s11, 5
	s_add_i32 s11, s11, s12
	s_lshl_b32 s12, s11, 3
	s_mulk_i32 s11, 0xb0
	s_sub_i32 s11, s10, s11
	s_lshr_b32 s10, s11, 3
	s_and_b32 s11, s11, 7
	s_add_i32 s12, s12, s11

;     __host__ __device__ bool next(int i, Unit& u) const {
;     ...
;         int wgid = (int)L; { const int q = nwg / NXCD, r = nwg % NXCD, xcd = wgid % NXCD, off = wgid / NXCD; wgid = (xcd < r ? xcd * (q + 1) : r * (q + 1) + (xcd - r) * q) + off; }
;         const int nig = WGM * nN, gid = wgid / nig, fm = gid * WGM, gsz = (nM - fm) < WGM ? (nM - fm) : WGM;
;         u.pm = fm + ((wgid % nig) % gsz); u.pn = (wgid % nig) / gsz; return true;
.LBB0_892:
	s_ashr_i32 s6, s30, 3
	s_add_i32 s6, s35, s6
	s_ashr_i32 s7, s6, 31
	s_lshr_b32 s7, s7, 27
	s_add_i32 s7, s6, s7
	s_ashr_i32 s30, s7, 5
	s_lshl_b32 s30, s30, 3
	s_andn2_b32 s7, s7, 31
	s_sub_i32 s6, s6, s7
	s_lshr_b32 s59, s6, 3
	s_and_b32 s6, s6, 7
	s_add_i32 s60, s30, s6
